# v9 stack + P6 row loop: per-row ssq reduction (load, 6-hop wave sum, rsq) moved below the issue of the row's 16 x/mix loads it does not feed (temporaries renamed to dead v150/v151, wait recounted to v
# speedup vs baseline: 1.0013x; 1.0013x over previous
; #define LAS __attribute__((address_space(3)))
; __device__ __forceinline__ void p6_rows(LAS unsigned char* lds_, const Params& p) {
;     ...
;         for (int r = r0 + F.wave; r < r1; r += NWAVES) {
;             const float rstd1 = rsqrtf(wave_sum(ssq[(size_t)r * 64 + F.lane]) * (1.0f / D) + EPS);
;             const float* xr = p.in[I_X] + (size_t)r * D; const bf16* mr = MIX + (size_t)r * D;
;             f32x4 v[16]; float ss = 0.f;
; #pragma unroll
;             for (int jg = 0; jg < 16; jg += 8) {
;                 v2u m2[8];
; #pragma unroll
;                 for (int j = 0; j < 8; ++j) { v[jg + j] = __builtin_nontemporal_load((const f32x4*)(xr + 256 * (jg + j) + 4 * F.lane)); m2[j] = __builtin_nontemporal_load((const v2u*)(mr + 256 * (jg + j) + 4 * F.lane)); }
; #pragma unroll
;                 for (int j = 0; j < 8; ++j) { const f32x4 a = *(LAS f32x4*)(cA + 256 * (jg + j) + 4 * F.lane);
;                     const f32x4 mx = (f32x4){bf_lo(m2[j].x), bf_hi(m2[j].x), bf_lo(m2[j].y), bf_hi(m2[j].y)};
;                     const f32x4 t = v[jg + j] + a * mx * rstd1; v[jg + j] = t; ss += (t[0] * t[0] + t[1] * t[1]) + (t[2] * t[2] + t[3] * t[3]);
;                     }
.LBB0_886:
	v_lshl_add_u64 v[2:3], s[96:97], 0, v[58:59]
	global_load_dword v150, v[2:3], off
	v_lshl_add_u64 v[64:65], s[96:97], 0, v[60:61]
	v_add_u32_e32 v122, 0, v18
	s_add_i32 s14, s14, 8
	v_lshl_add_u64 v[58:59], v[58:59], 0, s[6:7]
	v_lshl_add_u64 v[60:61], v[60:61], 0, s[12:13]
	s_cmp_ge_i32 s14, s30
	global_load_dwordx4 v[2:5], v[56:57], off nt
	v_add_co_u32_e32 v66, vcc, s24, v64
	s_nop 1
	v_addc_co_u32_e32 v67, vcc, 0, v65, vcc
	v_add_co_u32_e32 v98, vcc, s26, v64
	s_nop 1
	v_addc_co_u32_e32 v99, vcc, 0, v65, vcc
	global_load_dwordx2 v[70:71], v[98:99], off offset:-4096 nt
	global_load_dwordx4 v[6:9], v[56:57], off offset:1024 nt
	global_load_dwordx2 v[72:73], v[66:67], off offset:512 nt
	global_load_dwordx4 v[10:13], v[56:57], off offset:2048 nt
	global_load_dwordx2 v[74:75], v[66:67], off offset:1024 nt
	global_load_dwordx4 v[14:17], v[56:57], off offset:3072 nt
	global_load_dwordx2 v[76:77], v[66:67], off offset:1536 nt
	v_add_co_u32_e32 v68, vcc, s22, v56
	s_waitcnt vmcnt(6)
	v_lshlrev_b32_e32 v78, 16, v70
	v_addc_co_u32_e32 v69, vcc, 0, v57, vcc
	v_add_co_u32_e32 v100, vcc, s25, v56
	v_and_b32_e32 v79, 0xffff0000, v70
	s_nop 0
	v_addc_co_u32_e32 v101, vcc, 0, v57, vcc
	global_load_dwordx4 v[82:85], v[100:101], off offset:-4096 nt
	global_load_dwordx2 v[86:87], v[66:67], off offset:2048 nt
	global_load_dwordx4 v[88:91], v[68:69], off offset:1024 nt
	global_load_dwordx2 v[96:97], v[66:67], off offset:2560 nt
	global_load_dwordx4 v[92:95], v[68:69], off offset:2048 nt
	global_load_dwordx2 v[102:103], v[66:67], off offset:3072 nt
	global_load_dwordx4 v[104:107], v[68:69], off offset:3072 nt
	global_load_dwordx2 v[108:109], v[66:67], off offset:3584 nt
	s_waitcnt vmcnt(16)
	ds_bpermute_b32 v151, v116, v150
	s_waitcnt lgkmcnt(0)
	v_add_f32_e32 v150, v150, v151
	ds_bpermute_b32 v151, v117, v150
	s_waitcnt lgkmcnt(0)
	v_add_f32_e32 v150, v150, v151
	ds_bpermute_b32 v151, v118, v150
	s_waitcnt lgkmcnt(0)
	v_add_f32_e32 v150, v150, v151
	ds_bpermute_b32 v151, v119, v150
	s_waitcnt lgkmcnt(0)
	v_add_f32_e32 v150, v150, v151
	ds_bpermute_b32 v151, v120, v150
	s_waitcnt lgkmcnt(0)
	v_add_f32_e32 v150, v150, v151
	ds_bpermute_b32 v151, v121, v150
	s_waitcnt lgkmcnt(0)
	v_add_f32_e32 v150, v150, v151
	v_fmamk_f32 v150, v150, 0x39800000, v112
	v_cmp_gt_f32_e32 vcc, s23, v150
	v_mul_f32_e32 v151, 0x4b800000, v150
	s_nop 0
	v_cndmask_b32_e32 v150, v150, v151, vcc
	v_rsq_f32_e32 v150, v150
	s_nop 0
	v_mul_f32_e32 v151, 0x45800000, v150
	v_cndmask_b32_e32 v62, v150, v151, vcc
	ds_read_b128 v[66:69], v122
	v_lshlrev_b32_e32 v70, 16, v71
	v_and_b32_e32 v71, 0xffff0000, v71
	v_add_co_u32_e32 v136, vcc, s27, v56
	s_waitcnt lgkmcnt(0)
	v_pk_mul_f32 v[68:69], v[68:69], v[70:71]
	v_pk_mul_f32 v[66:67], v[66:67], v[78:79]
	v_pk_fma_f32 v[68:69], v[62:63], v[68:69], v[4:5] op_sel_hi:[0,1,1]
	v_pk_fma_f32 v[66:67], v[62:63], v[66:67], v[2:3] op_sel_hi:[0,1,1]
	v_pk_mul_f32 v[2:3], v[68:69], v[68:69]
	v_pk_mul_f32 v[4:5], v[66:67], v[66:67]
	v_addc_co_u32_e32 v137, vcc, 0, v57, vcc
	v_pk_mov_b32 v[70:71], v[4:5], v[2:3] op_sel:[1,0]
	v_mov_b32_e32 v5, v3
	v_pk_add_f32 v[110:111], v[70:71], v[4:5]
	ds_read_b128 v[2:5], v122 offset:1024
	s_waitcnt vmcnt(12)
	v_lshlrev_b32_e32 v70, 16, v72
	v_and_b32_e32 v71, 0xffff0000, v72
	v_lshlrev_b32_e32 v72, 16, v73
	v_and_b32_e32 v73, 0xffff0000, v73
	s_waitcnt lgkmcnt(0)
	v_pk_mul_f32 v[4:5], v[4:5], v[72:73]
	v_pk_mul_f32 v[2:3], v[2:3], v[70:71]
	v_pk_fma_f32 v[72:73], v[62:63], v[4:5], v[8:9] op_sel_hi:[0,1,1]
	v_pk_fma_f32 v[70:71], v[62:63], v[2:3], v[6:7] op_sel_hi:[0,1,1]
	v_pk_mul_f32 v[2:3], v[72:73], v[72:73]
	v_pk_mul_f32 v[4:5], v[70:71], v[70:71]
	s_waitcnt vmcnt(10)
	v_lshlrev_b32_e32 v8, 16, v74
	v_pk_mov_b32 v[6:7], v[4:5], v[2:3] op_sel:[1,0]
	v_mov_b32_e32 v5, v3
	v_pk_add_f32 v[6:7], v[6:7], v[4:5]
	ds_read_b128 v[2:5], v122 offset:2048
	v_and_b32_e32 v9, 0xffff0000, v74
	v_lshlrev_b32_e32 v74, 16, v75
	v_and_b32_e32 v75, 0xffff0000, v75
	v_lshl_add_u64 v[56:57], v[56:57], 0, s[0:1]
	s_waitcnt lgkmcnt(0)
	v_pk_mul_f32 v[2:3], v[2:3], v[8:9]
	v_pk_mul_f32 v[4:5], v[4:5], v[74:75]
	v_pk_fma_f32 v[78:79], v[62:63], v[2:3], v[10:11] op_sel_hi:[0,1,1]
	v_pk_fma_f32 v[74:75], v[62:63], v[4:5], v[12:13] op_sel_hi:[0,1,1]
	ds_read_b128 v[2:5], v122 offset:3072
	s_waitcnt vmcnt(8)
	v_lshlrev_b32_e32 v8, 16, v76
	v_and_b32_e32 v9, 0xffff0000, v76
	v_lshlrev_b32_e32 v10, 16, v77
	v_and_b32_e32 v11, 0xffff0000, v77
	s_waitcnt lgkmcnt(0)
	v_pk_mul_f32 v[2:3], v[2:3], v[8:9]
	v_pk_mul_f32 v[4:5], v[4:5], v[10:11]
	v_pk_fma_f32 v[80:81], v[62:63], v[2:3], v[14:15] op_sel_hi:[0,1,1]
	v_pk_fma_f32 v[76:77], v[62:63], v[4:5], v[16:17] op_sel_hi:[0,1,1]
	v_mul_f32_e32 v4, v80, v80
	v_pk_add_f32 v[2:3], v[110:111], v[110:111] op_sel:[0,1] op_sel_hi:[1,0]
	v_mul_f32_e32 v8, v81, v81
	v_mov_b32_e32 v3, v4
	v_pk_add_f32 v[4:5], v[6:7], v[6:7] op_sel:[0,1] op_sel_hi:[1,0]
	v_mul_f32_e32 v6, v75, v75
	v_mov_b32_e32 v5, v8
	v_pk_add_f32 v[2:3], v[2:3], v[4:5]
	v_mul_f32_e32 v4, v79, v79
	v_mul_f32_e32 v9, v76, v76
	v_mul_f32_e32 v10, v77, v77
	v_pk_fma_f32 v[4:5], v[78:79], v[78:79], v[4:5] op_sel_hi:[1,1,0]
	v_pk_fma_f32 v[6:7], v[74:75], v[74:75], v[6:7] op_sel_hi:[1,1,0]
	v_mov_b32_e32 v5, v9
	v_mov_b32_e32 v7, v10
	v_pk_add_f32 v[4:5], v[4:5], v[6:7]
	s_waitcnt vmcnt(6)
	v_lshlrev_b32_e32 v8, 16, v86
	v_pk_add_f32 v[6:7], v[2:3], v[4:5]
	ds_read_b128 v[2:5], v122 offset:4096
	v_and_b32_e32 v9, 0xffff0000, v86
	v_lshlrev_b32_e32 v10, 16, v87
	v_and_b32_e32 v11, 0xffff0000, v87
	s_waitcnt vmcnt(4)
	v_lshlrev_b32_e32 v12, 16, v97
	s_waitcnt lgkmcnt(0)
; #define LAS __attribute__((address_space(3)))
; __device__ __forceinline__ void p6_rows(LAS unsigned char* lds_, const Params& p) {
;     ...
;             for (int jg = 0; jg < 16; jg += 8) {
;                 v2u m2[8];
; #pragma unroll
;                 for (int j = 0; j < 8; ++j) { v[jg + j] = __builtin_nontemporal_load((const f32x4*)(xr + 256 * (jg + j) + 4 * F.lane)); m2[j] = __builtin_nontemporal_load((const v2u*)(mr + 256 * (jg + j) + 4 * F.lane)); }
; #pragma unroll
;                 for (int j = 0; j < 8; ++j) { const f32x4 a = *(LAS f32x4*)(cA + 256 * (jg + j) + 4 * F.lane);
;                     const f32x4 mx = (f32x4){bf_lo(m2[j].x), bf_hi(m2[j].x), bf_lo(m2[j].y), bf_hi(m2[j].y)};
;                     const f32x4 t = v[jg + j] + a * mx * rstd1; v[jg + j] = t; ss += (t[0] * t[0] + t[1] * t[1]) + (t[2] * t[2] + t[3] * t[3]);
;                     }
	v_pk_mul_f32 v[4:5], v[4:5], v[10:11]
	v_pk_mul_f32 v[2:3], v[2:3], v[8:9]
	v_pk_fma_f32 v[84:85], v[62:63], v[4:5], v[84:85] op_sel_hi:[0,1,1]
	v_pk_fma_f32 v[82:83], v[62:63], v[2:3], v[82:83] op_sel_hi:[0,1,1]
	v_pk_mul_f32 v[2:3], v[84:85], v[84:85]
	v_pk_mul_f32 v[4:5], v[82:83], v[82:83]
	v_lshlrev_b32_e32 v10, 16, v96
	v_pk_mov_b32 v[8:9], v[4:5], v[2:3] op_sel:[1,0]
	v_mov_b32_e32 v5, v3
	v_pk_add_f32 v[8:9], v[8:9], v[4:5]
	ds_read_b128 v[2:5], v122 offset:5120
	v_and_b32_e32 v11, 0xffff0000, v96
	v_and_b32_e32 v13, 0xffff0000, v97
	s_waitcnt lgkmcnt(0)
	v_pk_mul_f32 v[2:3], v[2:3], v[10:11]
	v_pk_mul_f32 v[4:5], v[4:5], v[12:13]
	s_waitcnt vmcnt(2)
	v_lshlrev_b32_e32 v10, 16, v102
	v_pk_fma_f32 v[86:87], v[62:63], v[4:5], v[90:91] op_sel_hi:[0,1,1]
	v_pk_fma_f32 v[90:91], v[62:63], v[2:3], v[88:89] op_sel_hi:[0,1,1]
	ds_read_b128 v[2:5], v122 offset:6144
	v_and_b32_e32 v11, 0xffff0000, v102
	v_lshlrev_b32_e32 v12, 16, v103
	v_and_b32_e32 v13, 0xffff0000, v103
	s_waitcnt lgkmcnt(0)
	v_pk_mul_f32 v[2:3], v[2:3], v[10:11]
	v_pk_mul_f32 v[4:5], v[4:5], v[12:13]
	v_pk_fma_f32 v[92:93], v[62:63], v[2:3], v[92:93] op_sel_hi:[0,1,1]
	v_pk_fma_f32 v[88:89], v[62:63], v[4:5], v[94:95] op_sel_hi:[0,1,1]
	v_mul_f32_e32 v4, v92, v92
	v_pk_add_f32 v[2:3], v[6:7], v[6:7] op_sel:[0,1] op_sel_hi:[1,0]
	v_mul_f32_e32 v10, v93, v93
	v_mov_b32_e32 v3, v4
	v_pk_add_f32 v[4:5], v[8:9], v[8:9] op_sel:[0,1] op_sel_hi:[1,0]
	v_mul_f32_e32 v6, v87, v87
	v_mov_b32_e32 v5, v10
	v_pk_add_f32 v[2:3], v[2:3], v[4:5]
	v_mul_f32_e32 v4, v91, v91
	v_mul_f32_e32 v11, v88, v88
	v_mul_f32_e32 v12, v89, v89
	v_pk_fma_f32 v[4:5], v[90:91], v[90:91], v[4:5] op_sel_hi:[1,1,0]
	v_pk_fma_f32 v[6:7], v[86:87], v[86:87], v[6:7] op_sel_hi:[1,1,0]
	v_mov_b32_e32 v5, v11
	v_mov_b32_e32 v7, v12
	v_pk_add_f32 v[4:5], v[4:5], v[6:7]
	s_waitcnt vmcnt(0)
	v_lshlrev_b32_e32 v6, 16, v108
	v_pk_add_f32 v[102:103], v[2:3], v[4:5]
	ds_read_b128 v[2:5], v122 offset:7168
	v_and_b32_e32 v7, 0xffff0000, v108
	v_lshlrev_b32_e32 v8, 16, v109
	v_and_b32_e32 v9, 0xffff0000, v109
	s_waitcnt lgkmcnt(0)
	v_pk_mul_f32 v[4:5], v[4:5], v[8:9]
	v_pk_mul_f32 v[2:3], v[2:3], v[6:7]
	v_pk_fma_f32 v[96:97], v[62:63], v[4:5], v[106:107] op_sel_hi:[0,1,1]
	v_pk_fma_f32 v[94:95], v[62:63], v[2:3], v[104:105] op_sel_hi:[0,1,1]
	v_pk_mul_f32 v[2:3], v[96:97], v[96:97]
	v_pk_mul_f32 v[4:5], v[94:95], v[94:95]
	s_nop 0
	v_pk_mov_b32 v[6:7], v[4:5], v[2:3] op_sel:[1,0]
	v_mov_b32_e32 v5, v3
	v_pk_add_f32 v[106:107], v[6:7], v[4:5]
	global_load_dwordx4 v[14:17], v[100:101], off nt
	global_load_dwordx2 v[110:111], v[98:99], off nt
	global_load_dwordx4 v[10:13], v[100:101], off offset:1024 nt
	global_load_dwordx2 v[108:109], v[98:99], off offset:512 nt
	global_load_dwordx4 v[6:9], v[100:101], off offset:2048 nt
	global_load_dwordx2 v[104:105], v[98:99], off offset:1024 nt
	global_load_dwordx4 v[2:5], v[100:101], off offset:3072 nt
	s_nop 0
	global_load_dwordx2 v[100:101], v[98:99], off offset:1536 nt
	global_load_dwordx4 v[124:127], v[136:137], off nt
	global_load_dwordx2 v[144:145], v[98:99], off offset:2048 nt
	global_load_dwordx4 v[128:131], v[136:137], off offset:1024 nt
	global_load_dwordx2 v[146:147], v[98:99], off offset:2560 nt
	global_load_dwordx4 v[132:135], v[136:137], off offset:2048 nt
	global_load_dwordx2 v[148:149], v[98:99], off offset:3072 nt
	s_nop 0
	global_load_dwordx4 v[136:139], v[136:137], off offset:3072 nt
	s_nop 0
	global_load_dwordx2 v[98:99], v[98:99], off offset:3584 nt
	ds_read_b128 v[140:143], v122 offset:8192
	s_waitcnt vmcnt(14)
	v_lshlrev_b32_e32 v150, 16, v110
	v_and_b32_e32 v151, 0xffff0000, v110
	v_lshlrev_b32_e32 v110, 16, v111
	v_and_b32_e32 v111, 0xffff0000, v111
	s_waitcnt lgkmcnt(0)
	v_pk_mul_f32 v[140:141], v[140:141], v[150:151]
	v_pk_mul_f32 v[110:111], v[142:143], v[110:111]
	v_pk_fma_f32 v[140:141], v[62:63], v[140:141], v[14:15] op_sel_hi:[0,1,1]
	v_pk_fma_f32 v[110:111], v[62:63], v[110:111], v[16:17] op_sel_hi:[0,1,1]
	ds_read_b128 v[14:17], v122 offset:9216
	s_waitcnt vmcnt(12)
	v_lshlrev_b32_e32 v142, 16, v108
	v_and_b32_e32 v143, 0xffff0000, v108
	v_lshlrev_b32_e32 v108, 16, v109
	v_and_b32_e32 v109, 0xffff0000, v109
	s_waitcnt lgkmcnt(0)
	v_pk_mul_f32 v[14:15], v[14:15], v[142:143]
	v_pk_mul_f32 v[16:17], v[16:17], v[108:109]
	v_pk_fma_f32 v[14:15], v[62:63], v[14:15], v[10:11] op_sel_hi:[0,1,1]
	v_pk_fma_f32 v[16:17], v[62:63], v[16:17], v[12:13] op_sel_hi:[0,1,1]
	v_mul_f32_e32 v12, v14, v14
	v_pk_add_f32 v[10:11], v[102:103], v[102:103] op_sel:[0,1] op_sel_hi:[1,0]
	v_mul_f32_e32 v108, v15, v15
	v_mov_b32_e32 v11, v12
	v_pk_add_f32 v[12:13], v[106:107], v[106:107] op_sel:[0,1] op_sel_hi:[1,0]
	v_mul_f32_e32 v102, v111, v111
	v_mov_b32_e32 v13, v108
	v_pk_add_f32 v[10:11], v[10:11], v[12:13]
	v_mul_f32_e32 v12, v141, v141
	v_mul_f32_e32 v109, v16, v16
	v_mul_f32_e32 v123, v17, v17
	v_pk_fma_f32 v[12:13], v[140:141], v[140:141], v[12:13] op_sel_hi:[1,1,0]
	v_pk_fma_f32 v[102:103], v[110:111], v[110:111], v[102:103] op_sel_hi:[1,1,0]
	v_mov_b32_e32 v13, v109
	v_mov_b32_e32 v103, v123
	v_pk_add_f32 v[12:13], v[12:13], v[102:103]
	s_waitcnt vmcnt(10)
	v_lshlrev_b32_e32 v106, 16, v104
	v_pk_add_f32 v[102:103], v[10:11], v[12:13]
	ds_read_b128 v[10:13], v122 offset:10240
	v_and_b32_e32 v107, 0xffff0000, v104
	v_lshlrev_b32_e32 v104, 16, v105
	v_and_b32_e32 v105, 0xffff0000, v105
	s_waitcnt lgkmcnt(0)
	v_pk_mul_f32 v[12:13], v[12:13], v[104:105]
	v_pk_mul_f32 v[10:11], v[10:11], v[106:107]
	v_pk_fma_f32 v[12:13], v[62:63], v[12:13], v[8:9] op_sel_hi:[0,1,1]
	v_pk_fma_f32 v[10:11], v[62:63], v[10:11], v[6:7] op_sel_hi:[0,1,1]
	v_pk_mul_f32 v[6:7], v[12:13], v[12:13]
	v_pk_mul_f32 v[8:9], v[10:11], v[10:11]
	s_waitcnt vmcnt(8)
; #define LAS __attribute__((address_space(3)))
; __device__ __forceinline__ void p6_rows(LAS unsigned char* lds_, const Params& p) {
;     ...
;             for (int jg = 0; jg < 16; jg += 8) {
;                 v2u m2[8];
; #pragma unroll
;                 for (int j = 0; j < 8; ++j) { v[jg + j] = __builtin_nontemporal_load((const f32x4*)(xr + 256 * (jg + j) + 4 * F.lane)); m2[j] = __builtin_nontemporal_load((const v2u*)(mr + 256 * (jg + j) + 4 * F.lane)); }
; #pragma unroll
;                 for (int j = 0; j < 8; ++j) { const f32x4 a = *(LAS f32x4*)(cA + 256 * (jg + j) + 4 * F.lane);
;                     const f32x4 mx = (f32x4){bf_lo(m2[j].x), bf_hi(m2[j].x), bf_lo(m2[j].y), bf_hi(m2[j].y)};
;                     const f32x4 t = v[jg + j] + a * mx * rstd1; v[jg + j] = t; ss += (t[0] * t[0] + t[1] * t[1]) + (t[2] * t[2] + t[3] * t[3]);
;                     }
;                 asm volatile("" ::: "memory");
;             }
;             const float rstd2 = rsqrtf(wave_sum(ss) * (1.0f / D) + EPS);
;             bf16* hrow = A1 + (size_t)r * D;
; #pragma unroll
;             for (int j = 0; j < 16; ++j) { const f32x4 b = *(LAS f32x4*)(cB + 256 * j + 4 * F.lane), c = *(LAS f32x4*)(cC + 256 * j + 4 * F.lane); const f32x4 o = v[j] * rstd2 * b + c;
	v_lshlrev_b32_e32 v106, 16, v100
	v_pk_mov_b32 v[104:105], v[8:9], v[6:7] op_sel:[1,0]
	v_mov_b32_e32 v9, v7
	v_pk_add_f32 v[104:105], v[104:105], v[8:9]
	ds_read_b128 v[6:9], v122 offset:11264
	v_and_b32_e32 v107, 0xffff0000, v100
	v_lshlrev_b32_e32 v100, 16, v101
	v_and_b32_e32 v101, 0xffff0000, v101
	s_waitcnt lgkmcnt(0)
	v_pk_mul_f32 v[6:7], v[6:7], v[106:107]
	v_pk_mul_f32 v[8:9], v[8:9], v[100:101]
	v_pk_fma_f32 v[106:107], v[62:63], v[6:7], v[2:3] op_sel_hi:[0,1,1]
	v_pk_fma_f32 v[100:101], v[62:63], v[8:9], v[4:5] op_sel_hi:[0,1,1]
	ds_read_b128 v[2:5], v122 offset:12288
	s_waitcnt vmcnt(6)
	v_lshlrev_b32_e32 v6, 16, v144
	v_and_b32_e32 v7, 0xffff0000, v144
	v_lshlrev_b32_e32 v8, 16, v145
	v_and_b32_e32 v9, 0xffff0000, v145
	s_waitcnt lgkmcnt(0)
	v_pk_mul_f32 v[2:3], v[2:3], v[6:7]
	v_pk_mul_f32 v[4:5], v[4:5], v[8:9]
	v_pk_fma_f32 v[124:125], v[62:63], v[2:3], v[124:125] op_sel_hi:[0,1,1]
	v_pk_fma_f32 v[108:109], v[62:63], v[4:5], v[126:127] op_sel_hi:[0,1,1]
	v_mul_f32_e32 v4, v124, v124
	v_pk_add_f32 v[2:3], v[102:103], v[102:103] op_sel:[0,1] op_sel_hi:[1,0]
	v_mul_f32_e32 v6, v125, v125
	v_mov_b32_e32 v3, v4
	v_pk_add_f32 v[4:5], v[104:105], v[104:105] op_sel:[0,1] op_sel_hi:[1,0]
	v_mul_f32_e32 v7, v108, v108
	v_mov_b32_e32 v5, v6
	v_pk_add_f32 v[2:3], v[2:3], v[4:5]
	v_mul_f32_e32 v4, v107, v107
	v_pk_fma_f32 v[4:5], v[106:107], v[106:107], v[4:5] op_sel_hi:[1,1,0]
	v_mul_f32_e32 v6, v101, v101
	v_mul_f32_e32 v8, v109, v109
	v_mov_b32_e32 v5, v7
	v_pk_fma_f32 v[6:7], v[100:101], v[100:101], v[6:7] op_sel_hi:[1,1,0]
	s_waitcnt vmcnt(4)
	v_and_b32_e32 v9, 0xffff0000, v146
	v_mov_b32_e32 v7, v8
	v_pk_add_f32 v[4:5], v[4:5], v[6:7]
	v_lshlrev_b32_e32 v8, 16, v146
	v_pk_add_f32 v[6:7], v[2:3], v[4:5]
	ds_read_b128 v[2:5], v122 offset:13312
	v_lshlrev_b32_e32 v102, 16, v147
	v_and_b32_e32 v103, 0xffff0000, v147
	s_waitcnt vmcnt(2)
	v_lshlrev_b32_e32 v126, 16, v148
	v_and_b32_e32 v127, 0xffff0000, v148
	s_waitcnt lgkmcnt(0)
	v_pk_mul_f32 v[4:5], v[4:5], v[102:103]
	v_pk_mul_f32 v[2:3], v[2:3], v[8:9]
	v_pk_fma_f32 v[104:105], v[62:63], v[4:5], v[130:131] op_sel_hi:[0,1,1]
	v_pk_fma_f32 v[102:103], v[62:63], v[2:3], v[128:129] op_sel_hi:[0,1,1]
	v_pk_mul_f32 v[2:3], v[104:105], v[104:105]
	v_pk_mul_f32 v[4:5], v[102:103], v[102:103]
	v_lshlrev_b32_e32 v128, 16, v149
	v_pk_mov_b32 v[8:9], v[4:5], v[2:3] op_sel:[1,0]
	v_mov_b32_e32 v5, v3
	v_pk_add_f32 v[8:9], v[8:9], v[4:5]
	ds_read_b128 v[2:5], v122 offset:14336
	v_and_b32_e32 v129, 0xffff0000, v149
	s_waitcnt vmcnt(0)
	v_lshlrev_b32_e32 v130, 16, v98
	v_and_b32_e32 v131, 0xffff0000, v98
	v_lshlrev_b32_e32 v98, 16, v99
	s_waitcnt lgkmcnt(0)
	v_pk_mul_f32 v[2:3], v[2:3], v[126:127]
	v_pk_mul_f32 v[4:5], v[4:5], v[128:129]
	v_pk_fma_f32 v[128:129], v[62:63], v[2:3], v[132:133] op_sel_hi:[0,1,1]
	v_pk_fma_f32 v[126:127], v[62:63], v[4:5], v[134:135] op_sel_hi:[0,1,1]
	ds_read_b128 v[2:5], v122 offset:15360
	v_and_b32_e32 v99, 0xffff0000, v99
	s_waitcnt lgkmcnt(0)
	v_pk_mul_f32 v[2:3], v[2:3], v[130:131]
	v_pk_mul_f32 v[4:5], v[4:5], v[98:99]
	v_pk_fma_f32 v[130:131], v[62:63], v[2:3], v[136:137] op_sel_hi:[0,1,1]
	v_pk_fma_f32 v[98:99], v[62:63], v[4:5], v[138:139] op_sel_hi:[0,1,1]
	v_mul_f32_e32 v4, v130, v130
	v_pk_add_f32 v[2:3], v[6:7], v[6:7] op_sel:[0,1] op_sel_hi:[1,0]
	v_mul_f32_e32 v62, v131, v131
	v_mov_b32_e32 v3, v4
	v_pk_add_f32 v[4:5], v[8:9], v[8:9] op_sel:[0,1] op_sel_hi:[1,0]
	v_mul_f32_e32 v6, v127, v127
	v_mov_b32_e32 v5, v62
	v_pk_add_f32 v[2:3], v[2:3], v[4:5]
	v_mul_f32_e32 v4, v129, v129
	v_mul_f32_e32 v123, v98, v98
	v_mul_f32_e32 v132, v99, v99
	v_pk_fma_f32 v[4:5], v[128:129], v[128:129], v[4:5] op_sel_hi:[1,1,0]
	v_pk_fma_f32 v[6:7], v[126:127], v[126:127], v[6:7] op_sel_hi:[1,1,0]
	v_mov_b32_e32 v5, v123
	v_mov_b32_e32 v7, v132
	v_pk_add_f32 v[4:5], v[4:5], v[6:7]
	s_nop 0
	v_pk_add_f32 v[2:3], v[2:3], v[4:5]
	s_nop 0
	v_add_f32_e32 v2, v2, v3
	ds_bpermute_b32 v3, v116, v2
	s_waitcnt lgkmcnt(0)
	v_add_f32_e32 v2, v2, v3
	ds_bpermute_b32 v3, v117, v2
	s_waitcnt lgkmcnt(0)
	v_add_f32_e32 v2, v2, v3
	ds_bpermute_b32 v3, v118, v2
	s_waitcnt lgkmcnt(0)
	v_add_f32_e32 v2, v2, v3
	ds_bpermute_b32 v3, v119, v2
	s_waitcnt lgkmcnt(0)
	v_add_f32_e32 v2, v2, v3
	ds_bpermute_b32 v3, v120, v2
	s_waitcnt lgkmcnt(0)
	v_add_f32_e32 v2, v2, v3
	ds_bpermute_b32 v3, v121, v2
	s_waitcnt lgkmcnt(0)
	v_add_f32_e32 v2, v2, v3
	v_fmamk_f32 v2, v2, 0x39800000, v112
	v_cmp_gt_f32_e32 vcc, s23, v2
	v_mul_f32_e32 v3, 0x4b800000, v2
	s_nop 0
	v_cndmask_b32_e32 v2, v2, v3, vcc
	v_rsq_f32_e32 v2, v2
	s_nop 0
	v_mul_f32_e32 v3, 0x45800000, v2
	v_cndmask_b32_e32 v62, v2, v3, vcc
	ds_read_b128 v[2:5], v122 offset:16384
	ds_read_b128 v[6:9], v122 offset:32768
	v_pk_mul_f32 v[66:67], v[66:67], v[62:63] op_sel_hi:[1,0]
	v_pk_mul_f32 v[68:69], v[68:69], v[62:63] op_sel_hi:[1,0]
	v_pk_mul_f32 v[14:15], v[14:15], v[62:63] op_sel_hi:[1,0]
	v_pk_mul_f32 v[16:17], v[16:17], v[62:63] op_sel_hi:[1,0]
	s_waitcnt lgkmcnt(0)
	v_pk_fma_f32 v[2:3], v[2:3], v[66:67], v[6:7]
	v_add_co_u32_e32 v66, vcc, s28, v64
	v_pk_fma_f32 v[4:5], v[4:5], v[68:69], v[8:9]
	s_nop 0
	v_addc_co_u32_e32 v67, vcc, 0, v65, vcc
	v_add_co_u32_e32 v64, vcc, s29, v64
	v_cvt_pk_bf16_f32 v2, v2, v3
	v_cvt_pk_bf16_f32 v3, v4, v5
	v_addc_co_u32_e32 v65, vcc, 0, v65, vcc
	global_store_dwordx2 v[64:65], v[2:3], off offset:-4096
	ds_read_b128 v[2:5], v122 offset:33792
	ds_read_b128 v[6:9], v122 offset:17408
	v_pk_mul_f32 v[68:69], v[70:71], v[62:63] op_sel_hi:[1,0]
	v_pk_mul_f32 v[70:71], v[72:73], v[62:63] op_sel_hi:[1,0]
	v_pk_mul_f32 v[10:11], v[10:11], v[62:63] op_sel_hi:[1,0]
	v_pk_mul_f32 v[12:13], v[12:13], v[62:63] op_sel_hi:[1,0]
	s_waitcnt lgkmcnt(0)
; #define LAS __attribute__((address_space(3)))
; __device__ __forceinline__ unsigned pk2(float lo, float hi) { const f32x2 v = {lo, hi}; return __builtin_bit_cast(unsigned, __builtin_convertvector(v, bf16x2_hw)); }
; __device__ __forceinline__ void p6_rows(LAS unsigned char* lds_, const Params& p) {
;     ...
; #pragma unroll
;             for (int j = 0; j < 16; ++j) { const f32x4 b = *(LAS f32x4*)(cB + 256 * j + 4 * F.lane), c = *(LAS f32x4*)(cC + 256 * j + 4 * F.lane); const f32x4 o = v[j] * rstd2 * b + c;
;                 v2u w; w.x = pk2(o[0], o[1]); w.y = pk2(o[2], o[3]); *(v2u*)(hrow + 256 * j + 4 * F.lane) = w; if ((j & 3) == 3) asm volatile("" ::: "memory"); }
;         }
	v_pk_fma_f32 v[4:5], v[8:9], v[70:71], v[4:5]
	v_pk_fma_f32 v[2:3], v[6:7], v[68:69], v[2:3]
	v_pk_mul_f32 v[68:69], v[78:79], v[62:63] op_sel_hi:[1,0]
	v_cvt_pk_bf16_f32 v2, v2, v3
	v_cvt_pk_bf16_f32 v3, v4, v5
	global_store_dwordx2 v[66:67], v[2:3], off offset:512
	ds_read_b128 v[2:5], v122 offset:34816
	ds_read_b128 v[6:9], v122 offset:18432
	v_pk_mul_f32 v[70:71], v[74:75], v[62:63] op_sel_hi:[1,0]
	s_waitcnt lgkmcnt(0)
	v_pk_fma_f32 v[2:3], v[6:7], v[68:69], v[2:3]
	v_pk_fma_f32 v[4:5], v[8:9], v[70:71], v[4:5]
	v_cvt_pk_bf16_f32 v2, v2, v3
	v_cvt_pk_bf16_f32 v3, v4, v5
	global_store_dwordx2 v[66:67], v[2:3], off offset:1024
	ds_read_b128 v[2:5], v122 offset:35840
	ds_read_b128 v[6:9], v122 offset:19456
	v_pk_mul_f32 v[68:69], v[80:81], v[62:63] op_sel_hi:[1,0]
	v_pk_mul_f32 v[70:71], v[76:77], v[62:63] op_sel_hi:[1,0]
	s_waitcnt lgkmcnt(0)
	v_pk_fma_f32 v[2:3], v[6:7], v[68:69], v[2:3]
	v_pk_fma_f32 v[4:5], v[8:9], v[70:71], v[4:5]
	v_cvt_pk_bf16_f32 v2, v2, v3
	v_cvt_pk_bf16_f32 v3, v4, v5
	global_store_dwordx2 v[66:67], v[2:3], off offset:1536
	ds_read_b128 v[2:5], v122 offset:20480
	ds_read_b128 v[6:9], v122 offset:36864
	v_pk_mul_f32 v[68:69], v[82:83], v[62:63] op_sel_hi:[1,0]
	v_pk_mul_f32 v[70:71], v[84:85], v[62:63] op_sel_hi:[1,0]
	s_waitcnt lgkmcnt(0)
	v_pk_fma_f32 v[2:3], v[2:3], v[68:69], v[6:7]
	v_pk_fma_f32 v[4:5], v[4:5], v[70:71], v[8:9]
	v_cvt_pk_bf16_f32 v2, v2, v3
	v_cvt_pk_bf16_f32 v3, v4, v5
	global_store_dwordx2 v[66:67], v[2:3], off offset:2048
	ds_read_b128 v[2:5], v122 offset:37888
	ds_read_b128 v[6:9], v122 offset:21504
	v_pk_mul_f32 v[68:69], v[90:91], v[62:63] op_sel_hi:[1,0]
	v_pk_mul_f32 v[70:71], v[86:87], v[62:63] op_sel_hi:[1,0]
	s_waitcnt lgkmcnt(0)
	v_pk_fma_f32 v[2:3], v[68:69], v[6:7], v[2:3]
	v_pk_fma_f32 v[4:5], v[70:71], v[8:9], v[4:5]
	v_cvt_pk_bf16_f32 v2, v2, v3
	v_cvt_pk_bf16_f32 v3, v4, v5
	global_store_dwordx2 v[66:67], v[2:3], off offset:2560
	ds_read_b128 v[2:5], v122 offset:38912
	ds_read_b128 v[6:9], v122 offset:22528
	v_pk_mul_f32 v[68:69], v[92:93], v[62:63] op_sel_hi:[1,0]
	v_pk_mul_f32 v[70:71], v[88:89], v[62:63] op_sel_hi:[1,0]
	s_waitcnt lgkmcnt(0)
	v_pk_fma_f32 v[2:3], v[68:69], v[6:7], v[2:3]
	v_pk_fma_f32 v[4:5], v[70:71], v[8:9], v[4:5]
	v_cvt_pk_bf16_f32 v2, v2, v3
	v_cvt_pk_bf16_f32 v3, v4, v5
	global_store_dwordx2 v[66:67], v[2:3], off offset:3072
	ds_read_b128 v[2:5], v122 offset:39936
	ds_read_b128 v[6:9], v122 offset:23552
	v_pk_mul_f32 v[68:69], v[94:95], v[62:63] op_sel_hi:[1,0]
	v_pk_mul_f32 v[70:71], v[96:97], v[62:63] op_sel_hi:[1,0]
	s_waitcnt lgkmcnt(0)
	v_pk_fma_f32 v[2:3], v[68:69], v[6:7], v[2:3]
	v_pk_fma_f32 v[4:5], v[70:71], v[8:9], v[4:5]
	v_cvt_pk_bf16_f32 v2, v2, v3
	v_cvt_pk_bf16_f32 v3, v4, v5
	global_store_dwordx2 v[66:67], v[2:3], off offset:3584
	ds_read_b128 v[2:5], v122 offset:24576
	ds_read_b128 v[6:9], v122 offset:40960
	v_pk_mul_f32 v[66:67], v[140:141], v[62:63] op_sel_hi:[1,0]
	v_pk_mul_f32 v[68:69], v[110:111], v[62:63] op_sel_hi:[1,0]
	s_waitcnt lgkmcnt(0)
	v_pk_fma_f32 v[2:3], v[66:67], v[2:3], v[6:7]
	v_pk_fma_f32 v[4:5], v[68:69], v[4:5], v[8:9]
	v_cvt_pk_bf16_f32 v2, v2, v3
	v_cvt_pk_bf16_f32 v3, v4, v5
	global_store_dwordx2 v[64:65], v[2:3], off
	ds_read_b128 v[2:5], v122 offset:41984
	ds_read_b128 v[6:9], v122 offset:25600
	s_waitcnt lgkmcnt(0)
	v_pk_fma_f32 v[4:5], v[16:17], v[8:9], v[4:5]
	v_pk_fma_f32 v[2:3], v[14:15], v[6:7], v[2:3]
	s_nop 0
	v_cvt_pk_bf16_f32 v2, v2, v3
	v_cvt_pk_bf16_f32 v3, v4, v5
	global_store_dwordx2 v[64:65], v[2:3], off offset:512
	ds_read_b128 v[2:5], v122 offset:43008
	ds_read_b128 v[6:9], v122 offset:26624
	s_waitcnt lgkmcnt(0)
	v_pk_fma_f32 v[4:5], v[12:13], v[8:9], v[4:5]
	v_pk_fma_f32 v[2:3], v[10:11], v[6:7], v[2:3]
	v_pk_mul_f32 v[10:11], v[106:107], v[62:63] op_sel_hi:[1,0]
	v_cvt_pk_bf16_f32 v2, v2, v3
	v_cvt_pk_bf16_f32 v3, v4, v5
	global_store_dwordx2 v[64:65], v[2:3], off offset:1024
	ds_read_b128 v[2:5], v122 offset:44032
	ds_read_b128 v[6:9], v122 offset:27648
	v_pk_mul_f32 v[12:13], v[100:101], v[62:63] op_sel_hi:[1,0]
	s_waitcnt lgkmcnt(0)
	v_pk_fma_f32 v[2:3], v[10:11], v[6:7], v[2:3]
	v_pk_fma_f32 v[4:5], v[12:13], v[8:9], v[4:5]
	v_cvt_pk_bf16_f32 v2, v2, v3
	v_cvt_pk_bf16_f32 v3, v4, v5
	global_store_dwordx2 v[64:65], v[2:3], off offset:1536
	ds_read_b128 v[2:5], v122 offset:28672
	ds_read_b128 v[6:9], v122 offset:45056
	v_pk_mul_f32 v[10:11], v[124:125], v[62:63] op_sel_hi:[1,0]
	v_pk_mul_f32 v[12:13], v[108:109], v[62:63] op_sel_hi:[1,0]
	s_waitcnt lgkmcnt(0)
	v_pk_fma_f32 v[2:3], v[10:11], v[2:3], v[6:7]
	v_pk_fma_f32 v[4:5], v[12:13], v[4:5], v[8:9]
	v_cvt_pk_bf16_f32 v2, v2, v3
	v_cvt_pk_bf16_f32 v3, v4, v5
	global_store_dwordx2 v[64:65], v[2:3], off offset:2048
	ds_read_b128 v[2:5], v122 offset:46080
	ds_read_b128 v[6:9], v122 offset:29696
	v_pk_mul_f32 v[10:11], v[102:103], v[62:63] op_sel_hi:[1,0]
	v_pk_mul_f32 v[12:13], v[104:105], v[62:63] op_sel_hi:[1,0]
	s_waitcnt lgkmcnt(0)
	v_pk_fma_f32 v[2:3], v[10:11], v[6:7], v[2:3]
	v_pk_fma_f32 v[4:5], v[12:13], v[8:9], v[4:5]
	v_cvt_pk_bf16_f32 v2, v2, v3
	v_cvt_pk_bf16_f32 v3, v4, v5
	global_store_dwordx2 v[64:65], v[2:3], off offset:2560
	ds_read_b128 v[2:5], v122 offset:47104
	ds_read_b128 v[6:9], v122 offset:30720
	v_pk_mul_f32 v[10:11], v[128:129], v[62:63] op_sel_hi:[1,0]
	v_pk_mul_f32 v[12:13], v[126:127], v[62:63] op_sel_hi:[1,0]
	s_waitcnt lgkmcnt(0)
	v_pk_fma_f32 v[2:3], v[10:11], v[6:7], v[2:3]
	v_pk_fma_f32 v[4:5], v[12:13], v[8:9], v[4:5]
	v_cvt_pk_bf16_f32 v2, v2, v3
	v_cvt_pk_bf16_f32 v3, v4, v5
	global_store_dwordx2 v[64:65], v[2:3], off offset:3072
	ds_read_b128 v[2:5], v122 offset:48128
	ds_read_b128 v[6:9], v122 offset:31744
	v_pk_mul_f32 v[10:11], v[130:131], v[62:63] op_sel_hi:[1,0]
	v_pk_mul_f32 v[12:13], v[98:99], v[62:63] op_sel_hi:[1,0]
	s_waitcnt lgkmcnt(0)
	v_pk_fma_f32 v[2:3], v[10:11], v[6:7], v[2:3]
	v_pk_fma_f32 v[4:5], v[12:13], v[8:9], v[4:5]
	v_cvt_pk_bf16_f32 v2, v2, v3
	v_cvt_pk_bf16_f32 v3, v4, v5
	global_store_dwordx2 v[64:65], v[2:3], off offset:3584
	s_cbranch_scc0 .LBB0_886
	s_branch .LBB0_883
